# static s_setprio 1 for waves 0-3 (older half) at entry, no per-phase flips
# speedup vs baseline: 1.0183x; 1.0057x over previous
; #define LAS __attribute__((address_space(3)))
; __global__ void __launch_bounds__(512, 2) hybrid_fwd(Params p) {
;     extern __shared__ __attribute__((aligned(16))) unsigned char shm[];
;     LAS unsigned char* lds = (LAS unsigned char*)shm;
;     cg::grid_group grid = cg::this_grid();
;     const int tid = threadIdx.x, G = gridDim.x;
;     unsigned char* ws = p.ws;
;     volatile LAS unsigned* ctlw = (volatile LAS unsigned*)(lds + 131072);
;     if (tid < 64) ctlw[tid] = 0u;
;     __syncthreads();
_Z10hybrid_fwd6Params:
	v_readfirstlane_b32 s98, v0
	s_nop 0
	s_and_b32 s98, s98, 0x3ff
	s_lshr_b32 s98, s98, 6
	s_cmp_lt_u32 s98, 4
	s_cbranch_scc0 .Lprio_done
	s_setprio 1
